# SGU phases: half of the workgroups start 5us later so HBM load bursts of the two halves interleave
# speedup vs baseline: 1.0802x; 1.0008x over previous
; __device__ __forceinline__ void kprep_phase(bf16_t* P, const float* kg, const float* rope, int tid, int bx, int G) {
;     const int stride = G * 512;
;     for (int base = bx * 512 + tid; base < MTOK * 16; base += 3 * stride) {
;         u32x4 w[3];
; #pragma unroll
;         for (int q = 0; q < 3; ++q) { const int idx = base + q * stride; if (idx < MTOK * 16) w[q] = *(const u32x4*)(P + (size_t)(idx >> 4) * EVEN_IN + 1536 + ((idx >> 3) & 1) * 64 + (idx & 7) * 8); }
; __global__ void __launch_bounds__(512, 2) fwd_kernel(Args a) {
;     ...
;         if (ph == 0) {
;             if (DG(0)) prologue(a, lds, tid, lane, wid);
;             __syncthreads();
;         } else {
;             const int layer = (ph - 1) >> 2, sub4 = (ph - 1) & 3, j = layer >> 1; const bool even = (layer & 1) == 0;
;             const int sub = (sub4 == 0) ? 0 : (sub4 == 1 ? 3 : sub4 - 1);
;             if (sub == 3) {
;                 kprep_phase(P, a.in[7] + j * 64, rope, tid, bx, G);
.LBB0_9:
	s_cmp_lt_i32 s13, 1
	s_cselect_b64 s[16:17], -1, 0
	s_and_b32 s8, s13, 3
	s_cmp_lg_u32 s8, 2
	s_cselect_b64 s[22:23], -1, 0
	s_or_b64 s[16:17], s[16:17], s[22:23]
	s_and_b64 vcc, exec, s[16:17]
	s_mov_b64 s[38:39], -1
	s_cbranch_vccz .LBB0_530
	s_waitcnt vmcnt(0)
	s_and_b32 vcc_lo, s13, 7
	s_cmp_lg_u32 vcc_lo, 7
	s_cbranch_scc1 .Lno_delay
	s_bitcmp1_b32 s2, 3
	s_cbranch_scc0 .Lno_delay
	s_sleep 127
.Lno_delay:
	v_sub_co_u32_e64 v0, s[16:17], s13, 1
	v_mov_b32_e32 v233, v199
	v_readfirstlane_b32 s37, v0
	s_andn2_b64 vcc, exec, s[16:17]
	v_and_b32_e32 v198, 63, v233
	v_writelane_b32 v255, s13, 49
	s_cbranch_vccz .LBB0_369
	s_and_b32 s8, s37, 3
	v_sub_co_u32_e64 v0, s[16:17], s8, 1
	s_cmp_lg_u32 s8, 1
	v_readfirstlane_b32 s8, v0
	s_cselect_b32 s8, s8, 3
	s_and_b64 s[16:17], s[16:17], exec
	s_cselect_b32 s45, 0, s8
	s_ashr_i32 s98, s37, 3
	s_bitcmp1_b32 s37, 2
	s_cselect_b64 s[8:9], -1, 0
	s_ashr_i32 s99, s98, 31
	v_writelane_b32 v255, s8, 50
	s_cmpk_lt_i32 s2, 0x300
	s_mov_b64 s[42:43], -1
	v_writelane_b32 v255, s9, 51
	s_cselect_b64 s[8:9], -1, 0
	v_writelane_b32 v255, s8, 52
	s_mov_b64 s[38:39], 0
	s_nop 0
	v_writelane_b32 v255, s9, 53
	s_ashr_i32 s8, s2, 31
	v_writelane_b32 v255, s8, 54
	s_lshr_b32 s8, s8, 29
	s_add_i32 s44, s2, s8
	s_and_b32 s8, s44, -8
	s_sub_i32 s28, s2, s8
	s_cmp_lt_i32 s28, 0
	s_cselect_b64 s[8:9], -1, 0
	v_writelane_b32 v255, s8, 55
	s_cmp_lt_i32 s45, 1
	s_nop 0
	v_writelane_b32 v255, s9, 56
	s_mov_b64 s[8:9], 0
	s_cbranch_scc1 .LBB0_142
	s_lshl_b32 s80, s98, 6
	s_ashr_i32 s81, s80, 31
	s_cmp_gt_i32 s45, 2
	s_mov_b64 s[38:39], -1
	s_cbranch_scc0 .LBB0_25
	v_lshl_add_u32 v26, s2, 9, v233
	s_mov_b32 s8, 0xc0000
	v_cmp_gt_i32_e32 vcc, s8, v26
	s_and_saveexec_b64 s[82:83], vcc
	v_readlane_b32 s22, v255, 19
	v_readlane_b32 s23, v255, 20
	s_cbranch_execz .LBB0_24
	v_cmp_lt_i32_e64 s[38:39], v222, v223
	s_lshl_b64 s[16:17], s[80:81], 2
	s_add_u32 s16, s62, s16
	v_cndmask_b32_e64 v1, v221, v222, s[38:39]
	v_cmp_lt_i32_e64 s[38:39], v224, v223
	v_lshlrev_b32_e32 v13, 2, v1
	v_and_b32_e32 v0, 7, v233
	v_cndmask_b32_e64 v1, v221, v224, s[38:39]
	v_cmp_lt_i32_e64 s[38:39], v225, v223
	v_lshlrev_b32_e32 v20, 2, v1
	s_addc_u32 s17, s63, s17
	v_cndmask_b32_e64 v1, v221, v225, s[38:39]
	v_cmp_gt_u32_e32 vcc, 4, v0
	v_lshlrev_b32_e32 v12, 3, v0
	v_lshlrev_b32_e32 v112, 5, v0
	v_mov_b32_e32 v0, 0
	v_lshlrev_b32_e32 v21, 2, v1
	v_lshlrev_b32_e32 v1, 3, v233
	v_lshl_add_u64 v[14:15], s[16:17], 0, v[112:113]
	v_lshl_add_u32 v22, s2, 12, v1
	s_mov_b64 s[84:85], 0
	v_mov_b32_e32 v1, v0
	v_mov_b32_e32 v2, v0
	v_mov_b32_e32 v3, v0
	v_mov_b32_e32 v4, v0
	v_mov_b32_e32 v5, v0
	v_mov_b32_e32 v6, v0
	v_mov_b32_e32 v7, v0
	s_branch .LBB0_16
